# DA loop: LDS-DMA in scalar-base form (running SGPR bases, constant 32-bit lane offsets): no per-tile 64-bit VALU address math
# speedup vs baseline: 1.0411x; 1.0029x over previous
; __device__ __forceinline__ void da_phase(LAS unsigned char* lds, const bf16* Q, const bf16* Kb, const bf16* Vb, bf16* O, const float* lq1, const float* lk1, const float* lq2, const float* lk2,
;                                          const float* t5, int G, int wave, int lane, int tid) {
;     ...
;         const char* kub = (const char*)Kb + (((size_t)h * T + tok0 + 32 * (wave & 1)) * 128 + (wave >> 2) * 64 + ((wave >> 1) & 1) * 32) * 2;
;         const char* vub = (const char*)Vb + (((size_t)h * T + tok0 + 16 * ((2 * wave) & 3)) * 128 + ((2 * wave) >> 2) * 32) * 2;
;         const unsigned kofs = (unsigned)(((lane >> 2) * 128 + ((lane & 3) ^ ((lane >> 4) & 3)) * 8) * 2);
;         const unsigned vofs = (unsigned)(((lane >> 2) * 128 + (lane & 3) * 8) * 2);
.LBB0_201:
	s_lshl_b32 s18, s38, 7
	v_readlane_b32 s0, v254, 47
	s_or_b32 s38, s18, s0
	s_mul_i32 s10, s36, 0x18000
	s_add_u32 s0, s10, s38
	s_addc_u32 s1, 0, 0
	s_add_u32 s0, s0, s14
	s_addc_u32 s1, s1, s15
	v_lshl_add_u64 v[2:3], s[0:1], 0, v[188:189]
	v_readlane_b32 s0, v254, 20
	s_add_u32 s0, s14, s0
	s_addc_u32 s1, s15, 0
	s_add_u32 s0, s0, s10
	s_addc_u32 s1, s1, 0
	s_lshl_b64 s[0:1], s[0:1], 8
	v_lshlrev_b64 v[2:3], 8, v[2:3]
	s_add_u32 s10, s34, s0
	v_lshl_add_u64 v[2:3], v[192:193], 0, v[2:3]
	s_addc_u32 s11, s35, s1
	s_mov_b32 m0, s3
	global_load_dwordx4 v[120:123], v[2:3], off
	global_load_dwordx4 v[124:127], v[2:3], off offset:32
	global_load_dwordx4 v[128:131], v[2:3], off offset:64
	global_load_dwordx4 v[132:135], v[2:3], off offset:96
	s_add_u32 s16, s30, s0
	v_lshl_add_u64 v[2:3], s[10:11], 0, v[194:195]
	s_addc_u32 s17, s31, s1
	global_load_lds_dwordx4 v[2:3], off
	v_lshl_add_u64 v[4:5], v[2:3], 0, s[62:63]
	s_add_i32 m0, s3, 0x400
	s_mov_b64 s[10:11], 0x4000
	global_load_lds_dwordx4 v[4:5], off
	v_lshl_add_u64 v[4:5], s[16:17], 0, v[196:197]
	s_add_i32 m0, s3, 0xc000
	v_lshl_add_u64 v[6:7], v[4:5], 0, s[62:63]
	global_load_lds_dwordx4 v[4:5], off
	s_add_i32 m0, s3, 0xc400
	s_mov_b64 s[16:17], 0x5000
	global_load_lds_dwordx4 v[6:7], off
	v_lshl_add_u64 v[6:7], v[2:3], 0, s[10:11]
	s_add_i32 m0, s3, 0x4000
	v_lshl_add_u64 v[2:3], v[2:3], 0, s[16:17]
	global_load_lds_dwordx4 v[6:7], off
	s_add_i32 m0, s3, 0x4400
	v_add_u32_e32 v0, s18, v228
	global_load_lds_dwordx4 v[2:3], off
	v_lshl_add_u64 v[2:3], v[4:5], 0, s[10:11]
	s_add_i32 s10, 0, 0x10000
	v_readlane_b32 s11, v254, 22
	s_add_i32 m0, s10, s11
	v_readlane_b32 s11, v254, 23
	v_lshl_add_u64 v[2:3], v[4:5], 0, s[16:17]
	s_add_i32 m0, s10, s11
	v_mov_b32_e32 v14, v1
	v_mov_b32_e32 v15, v1
	v_lshl_add_u64 v[202:203], v[198:199], 0, s[0:1]
	v_lshl_add_u64 v[204:205], v[200:201], 0, s[0:1]
	v_sub_u32_e32 v231, v219, v0
	v_readlane_b32 s0, v254, 48
	v_mov_b32_e32 v0, v1
	v_mov_b32_e32 v2, v1
	v_mov_b32_e32 v3, v1
	v_mov_b32_e32 v4, v1
	v_mov_b32_e32 v5, v1
	v_mov_b32_e32 v6, v1
	v_mov_b32_e32 v7, v1
	v_mov_b32_e32 v8, v1
	v_mov_b32_e32 v9, v1
	v_mov_b32_e32 v10, v1
	v_mov_b32_e32 v11, v1
	v_mov_b32_e32 v12, v1
	v_mov_b32_e32 v13, v1
	v_mov_b64_e32 v[30:31], v[14:15]
	v_mov_b64_e32 v[46:47], v[14:15]
	v_mov_b64_e32 v[62:63], v[14:15]
	v_mov_b64_e32 v[78:79], v[14:15]
	v_subrev_u32_e32 v230, s18, v227
	s_sub_i32 s40, s0, s18
	s_lshl_b32 s41, s39, 6
	s_mov_b32 s44, 0
	s_mov_b32 s50, -1
	v_mov_b32_e32 v232, 0
	s_mov_b64 s[16:17], 0
	s_mov_b32 s45, 2
	v_mov_b32_e32 v112, 0
	v_mov_b32_e32 v113, 0
	v_mov_b32_e32 v114, 0
	v_mov_b32_e32 v115, 0
	v_mov_b32_e32 v116, 0
	v_mov_b32_e32 v117, 0
	v_mov_b32_e32 v118, 0
	v_mov_b32_e32 v119, 0
	v_mov_b32_e32 v136, 0
	v_mov_b32_e32 v137, 0
	v_mov_b32_e32 v138, 0
	v_mov_b32_e32 v139, 0
	v_mov_b32_e32 v140, 0
	v_mov_b32_e32 v141, 0
	v_mov_b32_e32 v142, 0
	v_mov_b32_e32 v143, 0
	v_mov_b64_e32 v[28:29], v[12:13]
	v_mov_b64_e32 v[26:27], v[10:11]
	v_mov_b64_e32 v[24:25], v[8:9]
	v_mov_b64_e32 v[22:23], v[6:7]
	v_mov_b64_e32 v[20:21], v[4:5]
	v_mov_b64_e32 v[18:19], v[2:3]
	v_mov_b64_e32 v[16:17], v[0:1]
	v_mov_b64_e32 v[44:45], v[12:13]
	v_mov_b64_e32 v[42:43], v[10:11]
	v_mov_b64_e32 v[40:41], v[8:9]
	v_mov_b64_e32 v[38:39], v[6:7]
	v_mov_b64_e32 v[36:37], v[4:5]
	v_mov_b64_e32 v[34:35], v[2:3]
	v_mov_b64_e32 v[32:33], v[0:1]
	v_mov_b64_e32 v[60:61], v[12:13]
	v_mov_b64_e32 v[58:59], v[10:11]
	v_mov_b64_e32 v[56:57], v[8:9]
	v_mov_b64_e32 v[54:55], v[6:7]
	v_mov_b64_e32 v[52:53], v[4:5]
	v_mov_b64_e32 v[50:51], v[2:3]
	v_mov_b64_e32 v[48:49], v[0:1]
	v_mov_b64_e32 v[76:77], v[12:13]
	v_mov_b64_e32 v[74:75], v[10:11]
	v_mov_b64_e32 v[72:73], v[8:9]
	v_mov_b64_e32 v[70:71], v[6:7]
	v_mov_b64_e32 v[68:69], v[4:5]
	v_mov_b64_e32 v[66:67], v[2:3]
	v_mov_b64_e32 v[64:65], v[0:1]
	v_mov_b32_e32 v229, 0
	v_mov_b32_e32 v233, 0
	v_mov_b32_e32 v14, 0
	s_mov_b32 s46, 0
	s_mov_b32 s47, 2
	s_waitcnt vmcnt(0)
	s_barrier
	s_add_i32 s0, s40, s44
	s_cmpk_gt_i32 s0, 0x9e
	s_cselect_b32 s20, 2, 1
	s_cmpk_lt_i32 s0, 0xff42
	s_cselect_b64 s[0:1], -1, 0
	s_cmp_lg_u64 s[0:1], 0
	s_subb_u32 s51, s20, 0
	s_mov_b64 s[0:1], 0x1b208000
	v_lshl_add_u64 v[204:205], v[204:205], 0, s[0:1]
	s_mov_b64 s[0:1], 0x27204000
	v_lshl_add_u64 v[202:203], v[202:203], 0, s[0:1]
	s_nop 0
	v_readfirstlane_b32 s68, v204
	v_readfirstlane_b32 s69, v205
	v_readfirstlane_b32 s74, v202
	v_readfirstlane_b32 s75, v203
	v_add_u32_e32 v204, 0x1000, v194
	v_add_u32_e32 v205, 0x1000, v196
	s_mov_b32 s18, 0xff800000
	s_mov_b32 s21, 0
	v_add_u32_e32 v253, v216, v191
	v_add_u32_e32 v252, v216, v218
	ds_read_b128 v[172:175], v253
	ds_read_b128 v[176:179], v252
	ds_read_b128 v[168:171], v253 offset:4096
	ds_read_b128 v[164:167], v252 offset:4096
	s_waitcnt lgkmcnt(0)
	v_mov_b32_e32 v0, 0
	v_mov_b32_e32 v2, 0
	v_mov_b32_e32 v3, 0
	v_mov_b32_e32 v5, 0
	v_mov_b32_e32 v6, 0
	v_mov_b32_e32 v7, 0
	v_mov_b32_e32 v8, 0
	v_mov_b32_e32 v9, 0
	v_mov_b32_e32 v10, 0
	v_mov_b32_e32 v15, 0
	v_mov_b32_e32 v80, 0
	v_mov_b32_e32 v81, 0
	v_mov_b32_e32 v82, 0
	v_mov_b32_e32 v83, 0
	v_mov_b32_e32 v84, 0
	v_mov_b32_e32 v85, 0
	v_mov_b32_e32 v86, 0
	v_mov_b32_e32 v87, 0
	v_mov_b32_e32 v184, 0
	v_mov_b32_e32 v185, 0
	v_mov_b32_e32 v209, 0
	v_mov_b32_e32 v235, 0
	v_mov_b32_e32 v144, 0
	v_mov_b32_e32 v145, 0
	v_mov_b32_e32 v146, 0
	v_mov_b32_e32 v147, 0
	v_mov_b32_e32 v156, 0
	v_mov_b32_e32 v157, 0
	v_mov_b32_e32 v158, 0
	v_mov_b32_e32 v159, 0
	v_mov_b32_e32 v160, 0
	v_mov_b32_e32 v161, 0
	s_branch .LBB0_204

; __device__ __forceinline__ void da_phase(LAS unsigned char* lds, const bf16* Q, const bf16* Kb, const bf16* Vb, bf16* O, const float* lq1, const float* lk1, const float* lq2, const float* lk2,
;                                          const float* t5, int G, int wave, int lane, int tid) {
;     ...
;             if (t + 2 < NT) DA_DMA_K(t + 2, ks_n2);
;     ...
;             if (t + 2 < NT) DA_DMA_V(t + 2, (t + 2) & 3);
.LBB0_215:
	v_mfma_f32_32x32x16_bf16 v[96:111], v[172:175], v[120:123], v[236:251]
	ds_read_b128 v[172:175], v252 offset:2048
	v_cvt_pk_bf16_f32 v140, v0, v15
	v_cvt_pk_bf16_f32 v141, v156, v157
	v_cvt_pk_bf16_f32 v142, v158, v159
	v_cvt_pk_bf16_f32 v143, v160, v161
	v_mfma_f32_32x32x16_bf16 v[96:111], v[176:179], v[124:127], v[96:111]
	ds_read_b128 v[176:179], v253 offset:2048
	v_cvt_pk_bf16_f32 v136, v144, v145
	v_cvt_pk_bf16_f32 v137, v146, v147
	v_cvt_pk_bf16_f32 v138, v184, v185
	v_cvt_pk_bf16_f32 v139, v209, v235
	v_mfma_f32_32x32x16_bf16 v[96:111], v[168:171], v[128:131], v[96:111]
	ds_read_b128 v[168:171], v253 offset:6144
	v_cvt_pk_bf16_f32 v116, v80, v81
	v_cvt_pk_bf16_f32 v117, v82, v83
	v_cvt_pk_bf16_f32 v118, v84, v85
	v_cvt_pk_bf16_f32 v119, v86, v87
	v_mfma_f32_32x32x16_bf16 v[96:111], v[164:167], v[132:135], v[96:111]
	ds_read_b128 v[164:167], v252 offset:6144
	v_cvt_pk_bf16_f32 v112, v2, v3
	v_cvt_pk_bf16_f32 v113, v5, v6
	v_cvt_pk_bf16_f32 v114, v7, v8
	v_cvt_pk_bf16_f32 v115, v9, v10
	s_cmp_ge_u32 s45, s39
	s_cbranch_scc1 .LBB0_217
	s_lshl_b32 s0, s47, 14
	s_add_i32 m0, s3, s0
	s_nop 0
	global_load_lds_dwordx4 v194, s[68:69]
	s_add_i32 m0, m0, 0x400
	s_nop 0
	global_load_lds_dwordx4 v204, s[68:69]
	s_add_u32 s68, s68, 0x4000
	s_addc_u32 s69, s69, 0
.LBB0_217:
	s_waitcnt lgkmcnt(0)
	v_mfma_f32_32x32x16_bf16 v[80:95], v[176:179], v[120:123], v[236:251]
	ds_read_b64_tr_b16 v[160:161], v234 offset:0
	ds_read_b64_tr_b16 v[162:163], v234 offset:512
	ds_read_b64_tr_b16 v[156:157], v234 offset:1024
	ds_read_b64_tr_b16 v[158:159], v234 offset:1536
	v_max3_f32 v0, v96, v97, v98
	v_max3_f32 v0, v0, v99, v100
	v_mfma_f32_32x32x16_bf16 v[80:95], v[172:175], v[124:127], v[80:95]
	ds_read_b64_tr_b16 v[152:153], v234 offset:2048
	ds_read_b64_tr_b16 v[154:155], v234 offset:2560
	ds_read_b64_tr_b16 v[148:149], v234 offset:3072
	ds_read_b64_tr_b16 v[150:151], v234 offset:3584
	v_max3_f32 v0, v0, v101, v102
	v_max3_f32 v0, v0, v103, v104
	v_mfma_f32_32x32x16_bf16 v[80:95], v[168:171], v[128:131], v[80:95]
	ds_read_b64_tr_b16 v[144:145], v234 offset:4096
	ds_read_b64_tr_b16 v[146:147], v234 offset:4608
	ds_read_b64_tr_b16 v[10:11], v234 offset:5120
	ds_read_b64_tr_b16 v[12:13], v234 offset:5632
	v_max3_f32 v0, v0, v105, v106
	v_max3_f32 v0, v0, v107, v108
	v_mfma_f32_32x32x16_bf16 v[80:95], v[164:167], v[132:135], v[80:95]
	ds_read_b64_tr_b16 v[6:7], v234 offset:6144
	ds_read_b64_tr_b16 v[8:9], v234 offset:6656
	ds_read_b64_tr_b16 v[2:3], v234 offset:7168
	ds_read_b64_tr_b16 v[4:5], v234 offset:7680
	v_max_f32_e32 v0, v0, v0
	v_max_f32_e32 v15, v109, v109
	v_max_f32_e32 v0, v0, v15
	v_max3_f32 v0, v0, v110, v111
	s_cmp_gt_u32 s45, s39
	s_cbranch_scc1 .Lda_vskip
	s_add_i32 s0, s16, 0x4000
	s_and_b32 s0, s0, 0xc000
	s_add_i32 s20, s3, s0
	s_add_i32 m0, s20, 0xc000
	s_nop 0
	global_load_lds_dwordx4 v196, s[74:75]
	s_add_i32 m0, m0, 0x400
	s_nop 0
	global_load_lds_dwordx4 v205, s[74:75]
	s_add_u32 s74, s74, 0x4000
	s_addc_u32 s75, s75, 0

; __device__ __forceinline__ float half_swap_sum(float v) { auto rr = __builtin_amdgcn_permlane32_swap(__float_as_uint(v), __float_as_uint(v), false, false); return __uint_as_float(rr[0]) + __uint_as_float(rr[1]); }
; #define LGKM_WAIT(n) asm volatile("s_waitcnt lgkmcnt(" #n ")" ::: "memory")
; #define SCHED_FENCE() __builtin_amdgcn_sched_barrier(0)
; #define DA_VREADS(v, vaddr, DB) do { _Pragma("unroll") for (int k_ = 0; k_ < 4; ++k_) { DS_RDTR(v[2 * k_], vaddr, (DB) * 4096 + k_ * 1024); DS_RDTR(v[2 * k_ + 1], vaddr, (DB) * 4096 + k_ * 1024 + 512); } } while (0)
; #define DA_VMFMA(v, DB) do { _Pragma("unroll") for (int k_ = 0; k_ < 4; ++k_) { const H8 vf_ = (H8){v[2 * k_][0], v[2 * k_][1], v[2 * k_][2], v[2 * k_][3], v[2 * k_ + 1][0], v[2 * k_ + 1][1], v[2 * k_ + 1][2], v[2 * k_ + 1][3]}; \
;         o[DB] = __builtin_amdgcn_mfma_f32_32x32x16_bf16(__builtin_bit_cast(H8, pw[k_]), vf_, o[DB], 0, 0, 0); } } while (0)
; __device__ __forceinline__ void da_pv(F16 (&o)[4], const U4 (&pw)[4], S4 (&va)[8], S4 (&vb)[8], unsigned vaddr) {
;     LGKM_WAIT(0); SCHED_FENCE(); DA_VMFMA(va, 0); SCHED_FENCE();
;     DA_VREADS(va, vaddr, 2); SCHED_FENCE(); DA_VMFMA(vb, 1); SCHED_FENCE();
;     DA_VREADS(vb, vaddr, 3); LGKM_WAIT(8); SCHED_FENCE(); DA_VMFMA(va, 2); SCHED_FENCE();
;     LGKM_WAIT(0); SCHED_FENCE(); DA_VMFMA(vb, 3); SCHED_FENCE();
; }
; __device__ __forceinline__ void da_phase(LAS unsigned char* lds, const bf16* Q, const bf16* Kb, const bf16* Vb, bf16* O, const float* lq1, const float* lk1, const float* lq2, const float* lk2,
;                                          const float* t5, int G, int wave, int lane, int tid) {
;     ...
;         {   const unsigned vaddr = ldsb + VS + ((NT - 1) & 3) * 16384 + vlane; DA_VREADS(va, vaddr, 0); DA_VREADS(vb, vaddr, 1); da_pv(o, pw, va, vb, vaddr); }
;     ...
;         int lane_e = lane; asm volatile("" : "+v"(lane_e));
;         const int r32e = lane_e & 31, hie = lane_e >> 5;
;         const float lt = half_swap_sum(l);
;         if (hie == 0) wsf[r32e] = (comp == 0 ? 1.0f : -lam) / lt;
.LBB0_228:
	s_movk_i32 s75, 0xc1
	v_cvt_pk_bf16_f32 v140, v0, v15
	v_cvt_pk_bf16_f32 v141, v156, v157
	v_cvt_pk_bf16_f32 v142, v158, v159
	v_cvt_pk_bf16_f32 v143, v160, v161
	v_cvt_pk_bf16_f32 v136, v144, v145
	v_cvt_pk_bf16_f32 v137, v146, v147
	v_cvt_pk_bf16_f32 v138, v184, v185
	v_cvt_pk_bf16_f32 v139, v209, v235
	v_cvt_pk_bf16_f32 v116, v80, v81
	v_cvt_pk_bf16_f32 v117, v82, v83
	v_cvt_pk_bf16_f32 v118, v84, v85
	v_cvt_pk_bf16_f32 v119, v86, v87
	v_cvt_pk_bf16_f32 v112, v2, v3
	v_cvt_pk_bf16_f32 v113, v5, v6
	v_cvt_pk_bf16_f32 v114, v7, v8
	v_cvt_pk_bf16_f32 v115, v9, v10
	ds_read_b64_tr_b16 v[2:3], v221 offset:0
	ds_read_b64_tr_b16 v[4:5], v221 offset:512
	ds_read_b64_tr_b16 v[6:7], v221 offset:1024
	ds_read_b64_tr_b16 v[8:9], v221 offset:1536
	ds_read_b64_tr_b16 v[10:11], v221 offset:2048
	ds_read_b64_tr_b16 v[12:13], v221 offset:2560
	ds_read_b64_tr_b16 v[80:81], v221 offset:3072
	ds_read_b64_tr_b16 v[82:83], v221 offset:3584
	ds_read_b64_tr_b16 v[84:85], v221 offset:4096
	ds_read_b64_tr_b16 v[86:87], v221 offset:4608
	ds_read_b64_tr_b16 v[88:89], v221 offset:5120
	ds_read_b64_tr_b16 v[90:91], v221 offset:5632
	ds_read_b64_tr_b16 v[92:93], v221 offset:6144
	ds_read_b64_tr_b16 v[94:95], v221 offset:6656
	ds_read_b64_tr_b16 v[96:97], v221 offset:7168
	ds_read_b64_tr_b16 v[98:99], v221 offset:7680
	s_waitcnt lgkmcnt(0)
	s_nop 0
	v_mfma_f32_32x32x16_bf16 v[64:79], v[140:143], v[2:5], v[64:79]
	v_mfma_f32_32x32x16_bf16 v[64:79], v[136:139], v[6:9], v[64:79]
	v_mfma_f32_32x32x16_bf16 v[64:79], v[116:119], v[10:13], v[64:79]
	v_mfma_f32_32x32x16_bf16 v[64:79], v[112:115], v[80:83], v[64:79]
	ds_read_b64_tr_b16 v[2:3], v221 offset:8192
	ds_read_b64_tr_b16 v[4:5], v221 offset:8704
	ds_read_b64_tr_b16 v[6:7], v221 offset:9216
	ds_read_b64_tr_b16 v[8:9], v221 offset:9728
	ds_read_b64_tr_b16 v[10:11], v221 offset:10240
	ds_read_b64_tr_b16 v[12:13], v221 offset:10752
	ds_read_b64_tr_b16 v[80:81], v221 offset:11264
	ds_read_b64_tr_b16 v[82:83], v221 offset:11776
	v_mfma_f32_32x32x16_bf16 v[48:63], v[140:143], v[84:87], v[48:63]
	v_mfma_f32_32x32x16_bf16 v[48:63], v[136:139], v[88:91], v[48:63]
	v_mfma_f32_32x32x16_bf16 v[48:63], v[116:119], v[92:95], v[48:63]
	v_mfma_f32_32x32x16_bf16 v[48:63], v[112:115], v[96:99], v[48:63]
	ds_read_b64_tr_b16 v[84:85], v221 offset:12288
	ds_read_b64_tr_b16 v[86:87], v221 offset:12800
	ds_read_b64_tr_b16 v[88:89], v221 offset:13312
	ds_read_b64_tr_b16 v[90:91], v221 offset:13824
	ds_read_b64_tr_b16 v[92:93], v221 offset:14336
	ds_read_b64_tr_b16 v[94:95], v221 offset:14848
	ds_read_b64_tr_b16 v[96:97], v221 offset:15360
	ds_read_b64_tr_b16 v[98:99], v221 offset:15872
	s_waitcnt lgkmcnt(8)
	v_mfma_f32_32x32x16_bf16 v[32:47], v[140:143], v[2:5], v[32:47]
	v_mfma_f32_32x32x16_bf16 v[32:47], v[136:139], v[6:9], v[32:47]
	v_mfma_f32_32x32x16_bf16 v[32:47], v[116:119], v[10:13], v[32:47]
	v_mfma_f32_32x32x16_bf16 v[32:47], v[112:115], v[80:83], v[32:47]
	s_waitcnt lgkmcnt(0)
	v_mfma_f32_32x32x16_bf16 v[16:31], v[140:143], v[84:87], v[16:31]
	v_mfma_f32_32x32x16_bf16 v[16:31], v[136:139], v[88:91], v[16:31]
	v_mfma_f32_32x32x16_bf16 v[16:31], v[116:119], v[92:95], v[16:31]
	v_mfma_f32_32x32x16_bf16 v[16:31], v[112:115], v[96:99], v[16:31]
	v_mov_b32_e32 v0, v206
	v_mov_b32_e32 v2, v229
	s_nop 1
	v_permlane32_swap_b32_e32 v229, v2
	v_and_b32_e32 v126, 31, v0
	v_cmp_gt_u32_e32 vcc, 32, v0
	s_and_saveexec_b64 s[0:1], vcc
	s_cbranch_execz .LBB0_230
	v_add_f32_e32 v2, v229, v2
	v_div_scale_f32 v3, s[10:11], v2, v2, v222
	v_rcp_f32_e32 v4, v3
	v_div_scale_f32 v5, vcc, v222, v2, v222
	v_fma_f32 v6, -v3, v4, 1.0
	v_fmac_f32_e32 v4, v6, v4
	v_mul_f32_e32 v6, v5, v4
	v_fma_f32 v7, -v3, v6, v5
	v_fmac_f32_e32 v6, v7, v4
	v_fma_f32 v3, -v3, v6, v5
	v_div_fmas_f32 v3, v3, v4, v6
	v_div_fixup_f32 v2, v3, v2, v222
	v_lshl_add_u32 v3, v126, 2, s99
	ds_write_b32 v3, v2
